# cv17 + nt hint also on the bf16 weight stores of the conversion routine
# speedup vs baseline: 1.0080x; 1.0080x over previous
.Lcv_SA:
	s_waitcnt lgkmcnt(14)
	global_store_dwordx4 v17, v[214:217], s[22:23] nt
	s_add_u32 s22, s22, s24
	s_addc_u32 s23, s23, 0
	s_waitcnt lgkmcnt(12)
	global_store_dwordx4 v17, v[218:221], s[22:23] nt
	s_add_u32 s22, s22, s24
	s_addc_u32 s23, s23, 0
	s_waitcnt lgkmcnt(10)
	global_store_dwordx4 v17, v[222:225], s[22:23] nt
	s_add_u32 s22, s22, s24
	s_addc_u32 s23, s23, 0
	s_waitcnt lgkmcnt(8)
	global_store_dwordx4 v17, v[226:229], s[22:23] nt
	s_add_u32 s22, s22, s24
	s_addc_u32 s23, s23, 0
	s_waitcnt lgkmcnt(6)
	global_store_dwordx4 v17, v[230:233], s[22:23] nt
	s_add_u32 s22, s22, s24
	s_addc_u32 s23, s23, 0
	s_waitcnt lgkmcnt(4)
	global_store_dwordx4 v17, v[234:237], s[22:23] nt
	s_add_u32 s22, s22, s24
	s_addc_u32 s23, s23, 0
	s_waitcnt lgkmcnt(2)
	global_store_dwordx4 v17, v[238:241], s[22:23] nt
	s_add_u32 s22, s22, s24
	s_addc_u32 s23, s23, 0
	s_waitcnt lgkmcnt(0)
	global_store_dwordx4 v17, v[242:245], s[22:23] nt
	s_add_u32 s8, s8, s10
	s_cmp_ge_u32 s8, s9
	s_cbranch_scc1 .Lcv_exit

.Lcv_SB:
	s_waitcnt lgkmcnt(14)
	global_store_dwordx4 v17, v[214:217], s[22:23] nt
	s_add_u32 s22, s22, s24
	s_addc_u32 s23, s23, 0
	s_waitcnt lgkmcnt(12)
	global_store_dwordx4 v17, v[218:221], s[22:23] nt
	s_add_u32 s22, s22, s24
	s_addc_u32 s23, s23, 0
	s_waitcnt lgkmcnt(10)
	global_store_dwordx4 v17, v[222:225], s[22:23] nt
	s_add_u32 s22, s22, s24
	s_addc_u32 s23, s23, 0
	s_waitcnt lgkmcnt(8)
	global_store_dwordx4 v17, v[226:229], s[22:23] nt
	s_add_u32 s22, s22, s24
	s_addc_u32 s23, s23, 0
	s_waitcnt lgkmcnt(6)
	global_store_dwordx4 v17, v[230:233], s[22:23] nt
	s_add_u32 s22, s22, s24
	s_addc_u32 s23, s23, 0
	s_waitcnt lgkmcnt(4)
	global_store_dwordx4 v17, v[234:237], s[22:23] nt
	s_add_u32 s22, s22, s24
	s_addc_u32 s23, s23, 0
	s_waitcnt lgkmcnt(2)
	global_store_dwordx4 v17, v[238:241], s[22:23] nt
	s_add_u32 s22, s22, s24
	s_addc_u32 s23, s23, 0
	s_waitcnt lgkmcnt(0)
	global_store_dwordx4 v17, v[242:245], s[22:23] nt
	s_add_u32 s8, s8, s10
	s_cmp_ge_u32 s8, s9
	s_cbranch_scc1 .Lcv_exit
	s_branch .Lcv_WA

.Lcv_sl1_gd:
	global_load_dwordx4 v[100:103], v2, s[16:17] nt
	global_load_dwordx4 v[104:107], v3, s[16:17] nt
	s_add_u32 s16, s16, s20
	s_addc_u32 s17, s17, 0
	global_load_dwordx4 v[108:111], v2, s[16:17] nt
	global_load_dwordx4 v[112:115], v3, s[16:17] nt
	s_add_u32 s16, s16, s20
	s_addc_u32 s17, s17, 0
	global_load_dwordx4 v[116:119], v2, s[16:17] nt
	global_load_dwordx4 v[120:123], v3, s[16:17] nt
	s_add_u32 s16, s16, s20
	s_addc_u32 s17, s17, 0
	global_load_dwordx4 v[124:127], v2, s[16:17] nt
	global_load_dwordx4 v[128:131], v3, s[16:17] nt
	s_add_u32 s16, s16, s20
	s_addc_u32 s17, s17, 0
	global_load_dwordx4 v[132:135], v2, s[16:17] nt
	global_load_dwordx4 v[136:139], v3, s[16:17] nt
	s_add_u32 s16, s16, s20
	s_addc_u32 s17, s17, 0
	global_load_dwordx4 v[140:143], v2, s[16:17] nt
	global_load_dwordx4 v[144:147], v3, s[16:17] nt
	s_add_u32 s16, s16, s20
	s_addc_u32 s17, s17, 0
	global_load_dwordx4 v[148:151], v2, s[16:17] nt
	global_load_dwordx4 v[152:155], v3, s[16:17] nt
	s_add_u32 s16, s16, s20
	s_addc_u32 s17, s17, 0
	global_load_dwordx4 v[156:159], v2, s[16:17] nt
	global_load_dwordx4 v[160:163], v3, s[16:17] nt
	s_waitcnt vmcnt(16)
	v_pk_mul_f32 v[36:37], v[36:37], v[190:191] op_sel_hi:[1,0]
	v_pk_mul_f32 v[38:39], v[38:39], v[190:191] op_sel_hi:[1,0]
	v_pk_mul_f32 v[40:41], v[40:41], v[190:191] op_sel:[0,1] op_sel_hi:[1,1]
	v_pk_mul_f32 v[42:43], v[42:43], v[190:191] op_sel:[0,1] op_sel_hi:[1,1]
	v_cvt_pk_bf16_f32 v36, v36, v40
	v_cvt_pk_bf16_f32 v37, v37, v41
	v_cvt_pk_bf16_f32 v38, v38, v42
	v_cvt_pk_bf16_f32 v39, v39, v43
	ds_write_b64 v5, v[36:37] offset:0
	ds_write_b64 v5, v[38:39] offset:8
	v_pk_mul_f32 v[44:45], v[44:45], v[192:193] op_sel_hi:[1,0]
	v_pk_mul_f32 v[46:47], v[46:47], v[192:193] op_sel_hi:[1,0]
	v_pk_mul_f32 v[48:49], v[48:49], v[192:193] op_sel:[0,1] op_sel_hi:[1,1]
	v_pk_mul_f32 v[50:51], v[50:51], v[192:193] op_sel:[0,1] op_sel_hi:[1,1]
	v_cvt_pk_bf16_f32 v44, v44, v48
	v_cvt_pk_bf16_f32 v45, v45, v49
	v_cvt_pk_bf16_f32 v46, v46, v50
	v_cvt_pk_bf16_f32 v47, v47, v51
	ds_write_b64 v5, v[44:45] offset:1056
	ds_write_b64 v5, v[46:47] offset:1064
	v_pk_mul_f32 v[52:53], v[52:53], v[194:195] op_sel_hi:[1,0]
	v_pk_mul_f32 v[54:55], v[54:55], v[194:195] op_sel_hi:[1,0]
	v_pk_mul_f32 v[56:57], v[56:57], v[194:195] op_sel:[0,1] op_sel_hi:[1,1]
	v_pk_mul_f32 v[58:59], v[58:59], v[194:195] op_sel:[0,1] op_sel_hi:[1,1]
	v_cvt_pk_bf16_f32 v52, v52, v56
	v_cvt_pk_bf16_f32 v53, v53, v57
	v_cvt_pk_bf16_f32 v54, v54, v58
	v_cvt_pk_bf16_f32 v55, v55, v59
	ds_write_b64 v5, v[52:53] offset:2112
	ds_write_b64 v5, v[54:55] offset:2120
	v_pk_mul_f32 v[60:61], v[60:61], v[196:197] op_sel_hi:[1,0]
	v_pk_mul_f32 v[62:63], v[62:63], v[196:197] op_sel_hi:[1,0]
	v_pk_mul_f32 v[64:65], v[64:65], v[196:197] op_sel:[0,1] op_sel_hi:[1,1]
	v_pk_mul_f32 v[66:67], v[66:67], v[196:197] op_sel:[0,1] op_sel_hi:[1,1]
	v_cvt_pk_bf16_f32 v60, v60, v64
	v_cvt_pk_bf16_f32 v61, v61, v65
	v_cvt_pk_bf16_f32 v62, v62, v66
	v_cvt_pk_bf16_f32 v63, v63, v67
	ds_write_b64 v5, v[60:61] offset:3168
	ds_write_b64 v5, v[62:63] offset:3176
	v_pk_mul_f32 v[68:69], v[68:69], v[198:199] op_sel_hi:[1,0]
	v_pk_mul_f32 v[70:71], v[70:71], v[198:199] op_sel_hi:[1,0]
	v_pk_mul_f32 v[72:73], v[72:73], v[198:199] op_sel:[0,1] op_sel_hi:[1,1]
	v_pk_mul_f32 v[74:75], v[74:75], v[198:199] op_sel:[0,1] op_sel_hi:[1,1]
	v_cvt_pk_bf16_f32 v68, v68, v72
	v_cvt_pk_bf16_f32 v69, v69, v73
	v_cvt_pk_bf16_f32 v70, v70, v74
	v_cvt_pk_bf16_f32 v71, v71, v75
	ds_write_b64 v5, v[68:69] offset:4224
	ds_write_b64 v5, v[70:71] offset:4232
	v_pk_mul_f32 v[76:77], v[76:77], v[200:201] op_sel_hi:[1,0]
	v_pk_mul_f32 v[78:79], v[78:79], v[200:201] op_sel_hi:[1,0]
	v_pk_mul_f32 v[80:81], v[80:81], v[200:201] op_sel:[0,1] op_sel_hi:[1,1]
	v_pk_mul_f32 v[82:83], v[82:83], v[200:201] op_sel:[0,1] op_sel_hi:[1,1]
	v_cvt_pk_bf16_f32 v76, v76, v80
	v_cvt_pk_bf16_f32 v77, v77, v81
	v_cvt_pk_bf16_f32 v78, v78, v82
	v_cvt_pk_bf16_f32 v79, v79, v83
	ds_write_b64 v5, v[76:77] offset:5280
	ds_write_b64 v5, v[78:79] offset:5288
	v_pk_mul_f32 v[84:85], v[84:85], v[202:203] op_sel_hi:[1,0]
	v_pk_mul_f32 v[86:87], v[86:87], v[202:203] op_sel_hi:[1,0]
	v_pk_mul_f32 v[88:89], v[88:89], v[202:203] op_sel:[0,1] op_sel_hi:[1,1]
	v_pk_mul_f32 v[90:91], v[90:91], v[202:203] op_sel:[0,1] op_sel_hi:[1,1]
	v_cvt_pk_bf16_f32 v84, v84, v88
	v_cvt_pk_bf16_f32 v85, v85, v89
	v_cvt_pk_bf16_f32 v86, v86, v90
	v_cvt_pk_bf16_f32 v87, v87, v91
	ds_write_b64 v5, v[84:85] offset:6336
	ds_write_b64 v5, v[86:87] offset:6344
	v_pk_mul_f32 v[92:93], v[92:93], v[204:205] op_sel_hi:[1,0]
	v_pk_mul_f32 v[94:95], v[94:95], v[204:205] op_sel_hi:[1,0]
	v_pk_mul_f32 v[96:97], v[96:97], v[204:205] op_sel:[0,1] op_sel_hi:[1,1]
	v_pk_mul_f32 v[98:99], v[98:99], v[204:205] op_sel:[0,1] op_sel_hi:[1,1]
	v_cvt_pk_bf16_f32 v92, v92, v96
	v_cvt_pk_bf16_f32 v93, v93, v97
	v_cvt_pk_bf16_f32 v94, v94, v98
	v_cvt_pk_bf16_f32 v95, v95, v99
	ds_write_b64 v5, v[92:93] offset:7392
	ds_write_b64 v5, v[94:95] offset:7400
	s_waitcnt lgkmcnt(0)
	ds_read2_b32 v[214:215], v6 offset0:0 offset1:66
	ds_read2_b32 v[216:217], v6 offset0:132 offset1:198
	ds_read2_b32 v[218:219], v6 offset0:8 offset1:74
	ds_read2_b32 v[220:221], v6 offset0:140 offset1:206
	ds_read2_b32 v[222:223], v6 offset0:16 offset1:82
	ds_read2_b32 v[224:225], v6 offset0:148 offset1:214
	ds_read2_b32 v[226:227], v6 offset0:24 offset1:90
	ds_read2_b32 v[228:229], v6 offset0:156 offset1:222
	ds_read2_b32 v[230:231], v6 offset0:32 offset1:98
	ds_read2_b32 v[232:233], v6 offset0:164 offset1:230
	ds_read2_b32 v[234:235], v6 offset0:40 offset1:106
	ds_read2_b32 v[236:237], v6 offset0:172 offset1:238
	ds_read2_b32 v[238:239], v6 offset0:48 offset1:114
	ds_read2_b32 v[240:241], v6 offset0:180 offset1:246
	ds_read2_b32 v[242:243], v6 offset0:56 offset1:122
	ds_read2_b32 v[244:245], v6 offset0:188 offset1:254
	s_waitcnt lgkmcnt(14)
	global_store_dwordx4 v7, v[214:217], s[40:41] nt
	s_add_u32 s40, s40, s42
	s_addc_u32 s41, s41, 0
	s_waitcnt lgkmcnt(12)
	global_store_dwordx4 v7, v[218:221], s[40:41] nt
	s_add_u32 s40, s40, s42
	s_addc_u32 s41, s41, 0
	s_waitcnt lgkmcnt(10)
	global_store_dwordx4 v7, v[222:225], s[40:41] nt
	s_add_u32 s40, s40, s42
	s_addc_u32 s41, s41, 0
	s_waitcnt lgkmcnt(8)
	global_store_dwordx4 v7, v[226:229], s[40:41] nt
	s_add_u32 s40, s40, s42
	s_addc_u32 s41, s41, 0
	s_waitcnt lgkmcnt(6)
	global_store_dwordx4 v7, v[230:233], s[40:41] nt
	s_add_u32 s40, s40, s42
	s_addc_u32 s41, s41, 0
	s_waitcnt lgkmcnt(4)
	global_store_dwordx4 v7, v[234:237], s[40:41] nt
	s_add_u32 s40, s40, s42
	s_addc_u32 s41, s41, 0
	s_waitcnt lgkmcnt(2)
	global_store_dwordx4 v7, v[238:241], s[40:41] nt
	s_add_u32 s40, s40, s42
	s_addc_u32 s41, s41, 0
	s_waitcnt lgkmcnt(0)
	global_store_dwordx4 v7, v[242:245], s[40:41] nt
	s_mov_b32 s8, s11
	s_add_u32 s11, s8, s10
	s_cmp_ge_u32 s11, s9
	s_cbranch_scc1 .Lcv_slastB
	s_mov_b32 s12, 0
	s_mov_b32 s13, s11
	s_cmp_ge_u32 s13, 0x4180
	s_cbranch_scc0 .Lcv_sd2_l
	s_sub_u32 s13, s13, 0x4180
	s_add_u32 s12, s12, 1
	s_cmp_ge_u32 s13, 0x4180
	s_cbranch_scc0 .Lcv_sd2_l
	s_sub_u32 s13, s13, 0x4180
	s_add_u32 s12, s12, 1
	s_cmp_ge_u32 s13, 0x4180
	s_cbranch_scc0 .Lcv_sd2_l
	s_sub_u32 s13, s13, 0x4180
	s_add_u32 s12, s12, 1

.Lcv_sl2_gd:
	global_load_dwordx4 v[36:39], v2, s[16:17] nt
	global_load_dwordx4 v[40:43], v3, s[16:17] nt
	s_add_u32 s16, s16, s20
	s_addc_u32 s17, s17, 0
	global_load_dwordx4 v[44:47], v2, s[16:17] nt
	global_load_dwordx4 v[48:51], v3, s[16:17] nt
	s_add_u32 s16, s16, s20
	s_addc_u32 s17, s17, 0
	global_load_dwordx4 v[52:55], v2, s[16:17] nt
	global_load_dwordx4 v[56:59], v3, s[16:17] nt
	s_add_u32 s16, s16, s20
	s_addc_u32 s17, s17, 0
	global_load_dwordx4 v[60:63], v2, s[16:17] nt
	global_load_dwordx4 v[64:67], v3, s[16:17] nt
	s_add_u32 s16, s16, s20
	s_addc_u32 s17, s17, 0
	global_load_dwordx4 v[68:71], v2, s[16:17] nt
	global_load_dwordx4 v[72:75], v3, s[16:17] nt
	s_add_u32 s16, s16, s20
	s_addc_u32 s17, s17, 0
	global_load_dwordx4 v[76:79], v2, s[16:17] nt
	global_load_dwordx4 v[80:83], v3, s[16:17] nt
	s_add_u32 s16, s16, s20
	s_addc_u32 s17, s17, 0
	global_load_dwordx4 v[84:87], v2, s[16:17] nt
	global_load_dwordx4 v[88:91], v3, s[16:17] nt
	s_add_u32 s16, s16, s20
	s_addc_u32 s17, s17, 0
	global_load_dwordx4 v[92:95], v2, s[16:17] nt
	global_load_dwordx4 v[96:99], v3, s[16:17] nt
	s_waitcnt vmcnt(16)
	v_pk_mul_f32 v[100:101], v[100:101], v[18:19] op_sel_hi:[1,0]
	v_pk_mul_f32 v[102:103], v[102:103], v[18:19] op_sel_hi:[1,0]
	v_pk_mul_f32 v[104:105], v[104:105], v[18:19] op_sel:[0,1] op_sel_hi:[1,1]
	v_pk_mul_f32 v[106:107], v[106:107], v[18:19] op_sel:[0,1] op_sel_hi:[1,1]
	v_cvt_pk_bf16_f32 v100, v100, v104
	v_cvt_pk_bf16_f32 v101, v101, v105
	v_cvt_pk_bf16_f32 v102, v102, v106
	v_cvt_pk_bf16_f32 v103, v103, v107
	ds_write_b64 v5, v[100:101] offset:0
	ds_write_b64 v5, v[102:103] offset:8
	v_pk_mul_f32 v[108:109], v[108:109], v[20:21] op_sel_hi:[1,0]
	v_pk_mul_f32 v[110:111], v[110:111], v[20:21] op_sel_hi:[1,0]
	v_pk_mul_f32 v[112:113], v[112:113], v[20:21] op_sel:[0,1] op_sel_hi:[1,1]
	v_pk_mul_f32 v[114:115], v[114:115], v[20:21] op_sel:[0,1] op_sel_hi:[1,1]
	v_cvt_pk_bf16_f32 v108, v108, v112
	v_cvt_pk_bf16_f32 v109, v109, v113
	v_cvt_pk_bf16_f32 v110, v110, v114
	v_cvt_pk_bf16_f32 v111, v111, v115
	ds_write_b64 v5, v[108:109] offset:1056
	ds_write_b64 v5, v[110:111] offset:1064
	v_pk_mul_f32 v[116:117], v[116:117], v[22:23] op_sel_hi:[1,0]
	v_pk_mul_f32 v[118:119], v[118:119], v[22:23] op_sel_hi:[1,0]
	v_pk_mul_f32 v[120:121], v[120:121], v[22:23] op_sel:[0,1] op_sel_hi:[1,1]
	v_pk_mul_f32 v[122:123], v[122:123], v[22:23] op_sel:[0,1] op_sel_hi:[1,1]
	v_cvt_pk_bf16_f32 v116, v116, v120
	v_cvt_pk_bf16_f32 v117, v117, v121
	v_cvt_pk_bf16_f32 v118, v118, v122
	v_cvt_pk_bf16_f32 v119, v119, v123
	ds_write_b64 v5, v[116:117] offset:2112
	ds_write_b64 v5, v[118:119] offset:2120
	v_pk_mul_f32 v[124:125], v[124:125], v[24:25] op_sel_hi:[1,0]
	v_pk_mul_f32 v[126:127], v[126:127], v[24:25] op_sel_hi:[1,0]
	v_pk_mul_f32 v[128:129], v[128:129], v[24:25] op_sel:[0,1] op_sel_hi:[1,1]
	v_pk_mul_f32 v[130:131], v[130:131], v[24:25] op_sel:[0,1] op_sel_hi:[1,1]
	v_cvt_pk_bf16_f32 v124, v124, v128
	v_cvt_pk_bf16_f32 v125, v125, v129
	v_cvt_pk_bf16_f32 v126, v126, v130
	v_cvt_pk_bf16_f32 v127, v127, v131
	ds_write_b64 v5, v[124:125] offset:3168
	ds_write_b64 v5, v[126:127] offset:3176
	v_pk_mul_f32 v[132:133], v[132:133], v[26:27] op_sel_hi:[1,0]
	v_pk_mul_f32 v[134:135], v[134:135], v[26:27] op_sel_hi:[1,0]
	v_pk_mul_f32 v[136:137], v[136:137], v[26:27] op_sel:[0,1] op_sel_hi:[1,1]
	v_pk_mul_f32 v[138:139], v[138:139], v[26:27] op_sel:[0,1] op_sel_hi:[1,1]
	v_cvt_pk_bf16_f32 v132, v132, v136
	v_cvt_pk_bf16_f32 v133, v133, v137
	v_cvt_pk_bf16_f32 v134, v134, v138
	v_cvt_pk_bf16_f32 v135, v135, v139
	ds_write_b64 v5, v[132:133] offset:4224
	ds_write_b64 v5, v[134:135] offset:4232
	v_pk_mul_f32 v[140:141], v[140:141], v[28:29] op_sel_hi:[1,0]
	v_pk_mul_f32 v[142:143], v[142:143], v[28:29] op_sel_hi:[1,0]
	v_pk_mul_f32 v[144:145], v[144:145], v[28:29] op_sel:[0,1] op_sel_hi:[1,1]
	v_pk_mul_f32 v[146:147], v[146:147], v[28:29] op_sel:[0,1] op_sel_hi:[1,1]
	v_cvt_pk_bf16_f32 v140, v140, v144
	v_cvt_pk_bf16_f32 v141, v141, v145
	v_cvt_pk_bf16_f32 v142, v142, v146
	v_cvt_pk_bf16_f32 v143, v143, v147
	ds_write_b64 v5, v[140:141] offset:5280
	ds_write_b64 v5, v[142:143] offset:5288
	v_pk_mul_f32 v[148:149], v[148:149], v[30:31] op_sel_hi:[1,0]
	v_pk_mul_f32 v[150:151], v[150:151], v[30:31] op_sel_hi:[1,0]
	v_pk_mul_f32 v[152:153], v[152:153], v[30:31] op_sel:[0,1] op_sel_hi:[1,1]
	v_pk_mul_f32 v[154:155], v[154:155], v[30:31] op_sel:[0,1] op_sel_hi:[1,1]
	v_cvt_pk_bf16_f32 v148, v148, v152
	v_cvt_pk_bf16_f32 v149, v149, v153
	v_cvt_pk_bf16_f32 v150, v150, v154
	v_cvt_pk_bf16_f32 v151, v151, v155
	ds_write_b64 v5, v[148:149] offset:6336
	ds_write_b64 v5, v[150:151] offset:6344
	v_pk_mul_f32 v[156:157], v[156:157], v[32:33] op_sel_hi:[1,0]
	v_pk_mul_f32 v[158:159], v[158:159], v[32:33] op_sel_hi:[1,0]
	v_pk_mul_f32 v[160:161], v[160:161], v[32:33] op_sel:[0,1] op_sel_hi:[1,1]
	v_pk_mul_f32 v[162:163], v[162:163], v[32:33] op_sel:[0,1] op_sel_hi:[1,1]
	v_cvt_pk_bf16_f32 v156, v156, v160
	v_cvt_pk_bf16_f32 v157, v157, v161
	v_cvt_pk_bf16_f32 v158, v158, v162
	v_cvt_pk_bf16_f32 v159, v159, v163
	ds_write_b64 v5, v[156:157] offset:7392
	ds_write_b64 v5, v[158:159] offset:7400
	s_waitcnt lgkmcnt(0)
	ds_read2_b32 v[214:215], v6 offset0:0 offset1:66
	ds_read2_b32 v[216:217], v6 offset0:132 offset1:198
	ds_read2_b32 v[218:219], v6 offset0:8 offset1:74
	ds_read2_b32 v[220:221], v6 offset0:140 offset1:206
	ds_read2_b32 v[222:223], v6 offset0:16 offset1:82
	ds_read2_b32 v[224:225], v6 offset0:148 offset1:214
	ds_read2_b32 v[226:227], v6 offset0:24 offset1:90
	ds_read2_b32 v[228:229], v6 offset0:156 offset1:222
	ds_read2_b32 v[230:231], v6 offset0:32 offset1:98
	ds_read2_b32 v[232:233], v6 offset0:164 offset1:230
	ds_read2_b32 v[234:235], v6 offset0:40 offset1:106
	ds_read2_b32 v[236:237], v6 offset0:172 offset1:238
	ds_read2_b32 v[238:239], v6 offset0:48 offset1:114
	ds_read2_b32 v[240:241], v6 offset0:180 offset1:246
	ds_read2_b32 v[242:243], v6 offset0:56 offset1:122
	ds_read2_b32 v[244:245], v6 offset0:188 offset1:254
	s_waitcnt lgkmcnt(14)
	global_store_dwordx4 v12, v[214:217], s[44:45] nt
	s_add_u32 s44, s44, s46
	s_addc_u32 s45, s45, 0
	s_waitcnt lgkmcnt(12)
	global_store_dwordx4 v12, v[218:221], s[44:45] nt
	s_add_u32 s44, s44, s46
	s_addc_u32 s45, s45, 0
	s_waitcnt lgkmcnt(10)
	global_store_dwordx4 v12, v[222:225], s[44:45] nt
	s_add_u32 s44, s44, s46
	s_addc_u32 s45, s45, 0
	s_waitcnt lgkmcnt(8)
	global_store_dwordx4 v12, v[226:229], s[44:45] nt
	s_add_u32 s44, s44, s46
	s_addc_u32 s45, s45, 0
	s_waitcnt lgkmcnt(6)
	global_store_dwordx4 v12, v[230:233], s[44:45] nt
	s_add_u32 s44, s44, s46
	s_addc_u32 s45, s45, 0
	s_waitcnt lgkmcnt(4)
	global_store_dwordx4 v12, v[234:237], s[44:45] nt
	s_add_u32 s44, s44, s46
	s_addc_u32 s45, s45, 0
	s_waitcnt lgkmcnt(2)
	global_store_dwordx4 v12, v[238:241], s[44:45] nt
	s_add_u32 s44, s44, s46
	s_addc_u32 s45, s45, 0
	s_waitcnt lgkmcnt(0)
	global_store_dwordx4 v12, v[242:245], s[44:45] nt
	s_mov_b32 s8, s11
	s_branch .Lcv_sloop
.Lcv_slastA:
	s_waitcnt vmcnt(0)
	v_pk_mul_f32 v[36:37], v[36:37], v[190:191] op_sel_hi:[1,0]
	v_pk_mul_f32 v[38:39], v[38:39], v[190:191] op_sel_hi:[1,0]
	v_pk_mul_f32 v[40:41], v[40:41], v[190:191] op_sel:[0,1] op_sel_hi:[1,1]
	v_pk_mul_f32 v[42:43], v[42:43], v[190:191] op_sel:[0,1] op_sel_hi:[1,1]
	v_cvt_pk_bf16_f32 v36, v36, v40
	v_cvt_pk_bf16_f32 v37, v37, v41
	v_cvt_pk_bf16_f32 v38, v38, v42
	v_cvt_pk_bf16_f32 v39, v39, v43
	ds_write_b64 v5, v[36:37] offset:0
	ds_write_b64 v5, v[38:39] offset:8
	v_pk_mul_f32 v[44:45], v[44:45], v[192:193] op_sel_hi:[1,0]
	v_pk_mul_f32 v[46:47], v[46:47], v[192:193] op_sel_hi:[1,0]
	v_pk_mul_f32 v[48:49], v[48:49], v[192:193] op_sel:[0,1] op_sel_hi:[1,1]
	v_pk_mul_f32 v[50:51], v[50:51], v[192:193] op_sel:[0,1] op_sel_hi:[1,1]
	v_cvt_pk_bf16_f32 v44, v44, v48
	v_cvt_pk_bf16_f32 v45, v45, v49
	v_cvt_pk_bf16_f32 v46, v46, v50
	v_cvt_pk_bf16_f32 v47, v47, v51
	ds_write_b64 v5, v[44:45] offset:1056
	ds_write_b64 v5, v[46:47] offset:1064
	v_pk_mul_f32 v[52:53], v[52:53], v[194:195] op_sel_hi:[1,0]
	v_pk_mul_f32 v[54:55], v[54:55], v[194:195] op_sel_hi:[1,0]
	v_pk_mul_f32 v[56:57], v[56:57], v[194:195] op_sel:[0,1] op_sel_hi:[1,1]
	v_pk_mul_f32 v[58:59], v[58:59], v[194:195] op_sel:[0,1] op_sel_hi:[1,1]
	v_cvt_pk_bf16_f32 v52, v52, v56
	v_cvt_pk_bf16_f32 v53, v53, v57
	v_cvt_pk_bf16_f32 v54, v54, v58
	v_cvt_pk_bf16_f32 v55, v55, v59
	ds_write_b64 v5, v[52:53] offset:2112
	ds_write_b64 v5, v[54:55] offset:2120
	v_pk_mul_f32 v[60:61], v[60:61], v[196:197] op_sel_hi:[1,0]
	v_pk_mul_f32 v[62:63], v[62:63], v[196:197] op_sel_hi:[1,0]
	v_pk_mul_f32 v[64:65], v[64:65], v[196:197] op_sel:[0,1] op_sel_hi:[1,1]
	v_pk_mul_f32 v[66:67], v[66:67], v[196:197] op_sel:[0,1] op_sel_hi:[1,1]
	v_cvt_pk_bf16_f32 v60, v60, v64
	v_cvt_pk_bf16_f32 v61, v61, v65
	v_cvt_pk_bf16_f32 v62, v62, v66
	v_cvt_pk_bf16_f32 v63, v63, v67
	ds_write_b64 v5, v[60:61] offset:3168
	ds_write_b64 v5, v[62:63] offset:3176
	v_pk_mul_f32 v[68:69], v[68:69], v[198:199] op_sel_hi:[1,0]
	v_pk_mul_f32 v[70:71], v[70:71], v[198:199] op_sel_hi:[1,0]
	v_pk_mul_f32 v[72:73], v[72:73], v[198:199] op_sel:[0,1] op_sel_hi:[1,1]
	v_pk_mul_f32 v[74:75], v[74:75], v[198:199] op_sel:[0,1] op_sel_hi:[1,1]
	v_cvt_pk_bf16_f32 v68, v68, v72
	v_cvt_pk_bf16_f32 v69, v69, v73
	v_cvt_pk_bf16_f32 v70, v70, v74
	v_cvt_pk_bf16_f32 v71, v71, v75
	ds_write_b64 v5, v[68:69] offset:4224
	ds_write_b64 v5, v[70:71] offset:4232
	v_pk_mul_f32 v[76:77], v[76:77], v[200:201] op_sel_hi:[1,0]
	v_pk_mul_f32 v[78:79], v[78:79], v[200:201] op_sel_hi:[1,0]
	v_pk_mul_f32 v[80:81], v[80:81], v[200:201] op_sel:[0,1] op_sel_hi:[1,1]
	v_pk_mul_f32 v[82:83], v[82:83], v[200:201] op_sel:[0,1] op_sel_hi:[1,1]
	v_cvt_pk_bf16_f32 v76, v76, v80
	v_cvt_pk_bf16_f32 v77, v77, v81
	v_cvt_pk_bf16_f32 v78, v78, v82
	v_cvt_pk_bf16_f32 v79, v79, v83
	ds_write_b64 v5, v[76:77] offset:5280
	ds_write_b64 v5, v[78:79] offset:5288
	v_pk_mul_f32 v[84:85], v[84:85], v[202:203] op_sel_hi:[1,0]
	v_pk_mul_f32 v[86:87], v[86:87], v[202:203] op_sel_hi:[1,0]
	v_pk_mul_f32 v[88:89], v[88:89], v[202:203] op_sel:[0,1] op_sel_hi:[1,1]
	v_pk_mul_f32 v[90:91], v[90:91], v[202:203] op_sel:[0,1] op_sel_hi:[1,1]
	v_cvt_pk_bf16_f32 v84, v84, v88
	v_cvt_pk_bf16_f32 v85, v85, v89
	v_cvt_pk_bf16_f32 v86, v86, v90
	v_cvt_pk_bf16_f32 v87, v87, v91
	ds_write_b64 v5, v[84:85] offset:6336
	ds_write_b64 v5, v[86:87] offset:6344
	v_pk_mul_f32 v[92:93], v[92:93], v[204:205] op_sel_hi:[1,0]
	v_pk_mul_f32 v[94:95], v[94:95], v[204:205] op_sel_hi:[1,0]
	v_pk_mul_f32 v[96:97], v[96:97], v[204:205] op_sel:[0,1] op_sel_hi:[1,1]
	v_pk_mul_f32 v[98:99], v[98:99], v[204:205] op_sel:[0,1] op_sel_hi:[1,1]
	v_cvt_pk_bf16_f32 v92, v92, v96
	v_cvt_pk_bf16_f32 v93, v93, v97
	v_cvt_pk_bf16_f32 v94, v94, v98
	v_cvt_pk_bf16_f32 v95, v95, v99
	ds_write_b64 v5, v[92:93] offset:7392
	ds_write_b64 v5, v[94:95] offset:7400
	s_waitcnt lgkmcnt(0)
	ds_read2_b32 v[214:215], v6 offset0:0 offset1:66
	ds_read2_b32 v[216:217], v6 offset0:132 offset1:198
	ds_read2_b32 v[218:219], v6 offset0:8 offset1:74
	ds_read2_b32 v[220:221], v6 offset0:140 offset1:206
	ds_read2_b32 v[222:223], v6 offset0:16 offset1:82
	ds_read2_b32 v[224:225], v6 offset0:148 offset1:214
	ds_read2_b32 v[226:227], v6 offset0:24 offset1:90
	ds_read2_b32 v[228:229], v6 offset0:156 offset1:222
	ds_read2_b32 v[230:231], v6 offset0:32 offset1:98
	ds_read2_b32 v[232:233], v6 offset0:164 offset1:230
	ds_read2_b32 v[234:235], v6 offset0:40 offset1:106
	ds_read2_b32 v[236:237], v6 offset0:172 offset1:238
	ds_read2_b32 v[238:239], v6 offset0:48 offset1:114
	ds_read2_b32 v[240:241], v6 offset0:180 offset1:246
	ds_read2_b32 v[242:243], v6 offset0:56 offset1:122
	ds_read2_b32 v[244:245], v6 offset0:188 offset1:254
	s_waitcnt lgkmcnt(14)
	global_store_dwordx4 v7, v[214:217], s[40:41] nt
	s_add_u32 s40, s40, s42
	s_addc_u32 s41, s41, 0
	s_waitcnt lgkmcnt(12)
	global_store_dwordx4 v7, v[218:221], s[40:41] nt
	s_add_u32 s40, s40, s42
	s_addc_u32 s41, s41, 0
	s_waitcnt lgkmcnt(10)
	global_store_dwordx4 v7, v[222:225], s[40:41] nt
	s_add_u32 s40, s40, s42
	s_addc_u32 s41, s41, 0
	s_waitcnt lgkmcnt(8)
	global_store_dwordx4 v7, v[226:229], s[40:41] nt
	s_add_u32 s40, s40, s42
	s_addc_u32 s41, s41, 0
	s_waitcnt lgkmcnt(6)
	global_store_dwordx4 v7, v[230:233], s[40:41] nt
	s_add_u32 s40, s40, s42
	s_addc_u32 s41, s41, 0
	s_waitcnt lgkmcnt(4)
	global_store_dwordx4 v7, v[234:237], s[40:41] nt
	s_add_u32 s40, s40, s42
	s_addc_u32 s41, s41, 0
	s_waitcnt lgkmcnt(2)
	global_store_dwordx4 v7, v[238:241], s[40:41] nt
	s_add_u32 s40, s40, s42
	s_addc_u32 s41, s41, 0
	s_waitcnt lgkmcnt(0)
	global_store_dwordx4 v7, v[242:245], s[40:41] nt
	s_branch .Lcv_exit
.Lcv_slastB:
	s_waitcnt vmcnt(0)
	v_pk_mul_f32 v[100:101], v[100:101], v[18:19] op_sel_hi:[1,0]
	v_pk_mul_f32 v[102:103], v[102:103], v[18:19] op_sel_hi:[1,0]
	v_pk_mul_f32 v[104:105], v[104:105], v[18:19] op_sel:[0,1] op_sel_hi:[1,1]
	v_pk_mul_f32 v[106:107], v[106:107], v[18:19] op_sel:[0,1] op_sel_hi:[1,1]
	v_cvt_pk_bf16_f32 v100, v100, v104
	v_cvt_pk_bf16_f32 v101, v101, v105
	v_cvt_pk_bf16_f32 v102, v102, v106
	v_cvt_pk_bf16_f32 v103, v103, v107
	ds_write_b64 v5, v[100:101] offset:0
	ds_write_b64 v5, v[102:103] offset:8
	v_pk_mul_f32 v[108:109], v[108:109], v[20:21] op_sel_hi:[1,0]
	v_pk_mul_f32 v[110:111], v[110:111], v[20:21] op_sel_hi:[1,0]
	v_pk_mul_f32 v[112:113], v[112:113], v[20:21] op_sel:[0,1] op_sel_hi:[1,1]
	v_pk_mul_f32 v[114:115], v[114:115], v[20:21] op_sel:[0,1] op_sel_hi:[1,1]
	v_cvt_pk_bf16_f32 v108, v108, v112
	v_cvt_pk_bf16_f32 v109, v109, v113
	v_cvt_pk_bf16_f32 v110, v110, v114
	v_cvt_pk_bf16_f32 v111, v111, v115
	ds_write_b64 v5, v[108:109] offset:1056
	ds_write_b64 v5, v[110:111] offset:1064
	v_pk_mul_f32 v[116:117], v[116:117], v[22:23] op_sel_hi:[1,0]
	v_pk_mul_f32 v[118:119], v[118:119], v[22:23] op_sel_hi:[1,0]
	v_pk_mul_f32 v[120:121], v[120:121], v[22:23] op_sel:[0,1] op_sel_hi:[1,1]
	v_pk_mul_f32 v[122:123], v[122:123], v[22:23] op_sel:[0,1] op_sel_hi:[1,1]
	v_cvt_pk_bf16_f32 v116, v116, v120
	v_cvt_pk_bf16_f32 v117, v117, v121
	v_cvt_pk_bf16_f32 v118, v118, v122
	v_cvt_pk_bf16_f32 v119, v119, v123
	ds_write_b64 v5, v[116:117] offset:2112
	ds_write_b64 v5, v[118:119] offset:2120
	v_pk_mul_f32 v[124:125], v[124:125], v[24:25] op_sel_hi:[1,0]
	v_pk_mul_f32 v[126:127], v[126:127], v[24:25] op_sel_hi:[1,0]
	v_pk_mul_f32 v[128:129], v[128:129], v[24:25] op_sel:[0,1] op_sel_hi:[1,1]
	v_pk_mul_f32 v[130:131], v[130:131], v[24:25] op_sel:[0,1] op_sel_hi:[1,1]
	v_cvt_pk_bf16_f32 v124, v124, v128
	v_cvt_pk_bf16_f32 v125, v125, v129
	v_cvt_pk_bf16_f32 v126, v126, v130
	v_cvt_pk_bf16_f32 v127, v127, v131
	ds_write_b64 v5, v[124:125] offset:3168
	ds_write_b64 v5, v[126:127] offset:3176
	v_pk_mul_f32 v[132:133], v[132:133], v[26:27] op_sel_hi:[1,0]
	v_pk_mul_f32 v[134:135], v[134:135], v[26:27] op_sel_hi:[1,0]
	v_pk_mul_f32 v[136:137], v[136:137], v[26:27] op_sel:[0,1] op_sel_hi:[1,1]
	v_pk_mul_f32 v[138:139], v[138:139], v[26:27] op_sel:[0,1] op_sel_hi:[1,1]
	v_cvt_pk_bf16_f32 v132, v132, v136
	v_cvt_pk_bf16_f32 v133, v133, v137
	v_cvt_pk_bf16_f32 v134, v134, v138
	v_cvt_pk_bf16_f32 v135, v135, v139
	ds_write_b64 v5, v[132:133] offset:4224
	ds_write_b64 v5, v[134:135] offset:4232
	v_pk_mul_f32 v[140:141], v[140:141], v[28:29] op_sel_hi:[1,0]
	v_pk_mul_f32 v[142:143], v[142:143], v[28:29] op_sel_hi:[1,0]
	v_pk_mul_f32 v[144:145], v[144:145], v[28:29] op_sel:[0,1] op_sel_hi:[1,1]
	v_pk_mul_f32 v[146:147], v[146:147], v[28:29] op_sel:[0,1] op_sel_hi:[1,1]
	v_cvt_pk_bf16_f32 v140, v140, v144
	v_cvt_pk_bf16_f32 v141, v141, v145
	v_cvt_pk_bf16_f32 v142, v142, v146
	v_cvt_pk_bf16_f32 v143, v143, v147
	ds_write_b64 v5, v[140:141] offset:5280
	ds_write_b64 v5, v[142:143] offset:5288
	v_pk_mul_f32 v[148:149], v[148:149], v[30:31] op_sel_hi:[1,0]
	v_pk_mul_f32 v[150:151], v[150:151], v[30:31] op_sel_hi:[1,0]
	v_pk_mul_f32 v[152:153], v[152:153], v[30:31] op_sel:[0,1] op_sel_hi:[1,1]
	v_pk_mul_f32 v[154:155], v[154:155], v[30:31] op_sel:[0,1] op_sel_hi:[1,1]
	v_cvt_pk_bf16_f32 v148, v148, v152
	v_cvt_pk_bf16_f32 v149, v149, v153
	v_cvt_pk_bf16_f32 v150, v150, v154
	v_cvt_pk_bf16_f32 v151, v151, v155
	ds_write_b64 v5, v[148:149] offset:6336
	ds_write_b64 v5, v[150:151] offset:6344
	v_pk_mul_f32 v[156:157], v[156:157], v[32:33] op_sel_hi:[1,0]
	v_pk_mul_f32 v[158:159], v[158:159], v[32:33] op_sel_hi:[1,0]
	v_pk_mul_f32 v[160:161], v[160:161], v[32:33] op_sel:[0,1] op_sel_hi:[1,1]
	v_pk_mul_f32 v[162:163], v[162:163], v[32:33] op_sel:[0,1] op_sel_hi:[1,1]
	v_cvt_pk_bf16_f32 v156, v156, v160
	v_cvt_pk_bf16_f32 v157, v157, v161
	v_cvt_pk_bf16_f32 v158, v158, v162
	v_cvt_pk_bf16_f32 v159, v159, v163
	ds_write_b64 v5, v[156:157] offset:7392
	ds_write_b64 v5, v[158:159] offset:7400
	s_waitcnt lgkmcnt(0)
	ds_read2_b32 v[214:215], v6 offset0:0 offset1:66
	ds_read2_b32 v[216:217], v6 offset0:132 offset1:198
	ds_read2_b32 v[218:219], v6 offset0:8 offset1:74
	ds_read2_b32 v[220:221], v6 offset0:140 offset1:206
	ds_read2_b32 v[222:223], v6 offset0:16 offset1:82
	ds_read2_b32 v[224:225], v6 offset0:148 offset1:214
	ds_read2_b32 v[226:227], v6 offset0:24 offset1:90
	ds_read2_b32 v[228:229], v6 offset0:156 offset1:222
	ds_read2_b32 v[230:231], v6 offset0:32 offset1:98
	ds_read2_b32 v[232:233], v6 offset0:164 offset1:230
	ds_read2_b32 v[234:235], v6 offset0:40 offset1:106
	ds_read2_b32 v[236:237], v6 offset0:172 offset1:238
	ds_read2_b32 v[238:239], v6 offset0:48 offset1:114
	ds_read2_b32 v[240:241], v6 offset0:180 offset1:246
	ds_read2_b32 v[242:243], v6 offset0:56 offset1:122
	ds_read2_b32 v[244:245], v6 offset0:188 offset1:254
	s_waitcnt lgkmcnt(14)
	global_store_dwordx4 v12, v[214:217], s[44:45] nt
	s_add_u32 s44, s44, s46
	s_addc_u32 s45, s45, 0
	s_waitcnt lgkmcnt(12)
	global_store_dwordx4 v12, v[218:221], s[44:45] nt
	s_add_u32 s44, s44, s46
	s_addc_u32 s45, s45, 0
	s_waitcnt lgkmcnt(10)
	global_store_dwordx4 v12, v[222:225], s[44:45] nt
	s_add_u32 s44, s44, s46
	s_addc_u32 s45, s45, 0
	s_waitcnt lgkmcnt(8)
	global_store_dwordx4 v12, v[226:229], s[44:45] nt
	s_add_u32 s44, s44, s46
	s_addc_u32 s45, s45, 0
	s_waitcnt lgkmcnt(6)
	global_store_dwordx4 v12, v[230:233], s[44:45] nt
	s_add_u32 s44, s44, s46
	s_addc_u32 s45, s45, 0
	s_waitcnt lgkmcnt(4)
	global_store_dwordx4 v12, v[234:237], s[44:45] nt
	s_add_u32 s44, s44, s46
	s_addc_u32 s45, s45, 0
	s_waitcnt lgkmcnt(2)
	global_store_dwordx4 v12, v[238:241], s[44:45] nt
	s_add_u32 s44, s44, s46
	s_addc_u32 s45, s45, 0
	s_waitcnt lgkmcnt(0)
	global_store_dwordx4 v12, v[242:245], s[44:45] nt
